# w_out/ff2 phase start: K-loop prologue DMA issued before the LayerNorm stats-table reduce so the two latencies overlap (single-unit path)
# baseline (speedup 1.0000x reference)
.Lst_skip_wo:
	v_readlane_b32 s100, v255, 10
	v_readlane_b32 s101, v255, 11
	s_ashr_i32 s43, s42, 31
	s_lshl_b64 s[44:45], s[42:43], 21
	v_cndmask_b32_e64 v0, 0, 1, s[100:101]
	v_cmp_ne_u32_e64 s[12:13], 1, v0
	v_readfirstlane_b32 s43, v244
	v_and_b32_e32 v245, 15, v244
	v_writelane_b32 v255, s12, 57
	s_andn2_b64 vcc, exec, s[100:101]
	s_nop 0
	v_writelane_b32 v255, s13, 58
	s_cbranch_vccnz .Lpo_old_wo
	v_lshlrev_b32_e32 v3, 4, v244
	v_add_u32_e32 v1, 0x2000, v3
	v_ashrrev_i32_e32 v0, 31, v1
	v_lshrrev_b32_e32 v0, 22, v0
	v_add_u32_e32 v0, v1, v0
	v_ashrrev_i32_e32 v0, 10, v0
	v_mul_i32_i24_e32 v2, 0x400, v0
	v_sub_u32_e32 v1, v1, v2
	v_lshrrev_b32_e32 v2, 4, v1
	s_ashr_i32 s17, s43, 6
	v_bitop3_b32 v2, v2, v1, 32 bitop3:0x6c
	s_ashr_i32 s16, s43, 8
	s_lshl_b32 s58, s17, 10
	v_ashrrev_i32_e32 v1, 31, v2
	s_add_u32 s59, s40, 0x4a40000
	v_lshrrev_b32_e32 v1, 26, v1
	s_addc_u32 s62, s41, 0
	v_add_u32_e32 v4, v2, v1
	v_lshlrev_b32_e32 v5, 3, v0
	s_add_u32 s10, s40, s44
	v_ashrrev_i32_e32 v1, 6, v4
	v_and_b32_e32 v5, -16, v5
	s_addc_u32 s11, s41, s45
	v_add_u32_e32 v5, v1, v5
	s_add_u32 s63, s10, 0x600000
	v_and_b32_e32 v6, 3, v1
	s_mov_b32 s10, 0x1fffe0
	v_lshrrev_b32_e32 v7, 2, v5
	v_lshlrev_b32_e32 v8, 1, v5
	v_and_b32_e32 v4, 0xc0, v4
	v_and_or_b32 v6, v5, s10, v6
	v_and_b32_e32 v7, 4, v7
	v_and_b32_e32 v8, 24, v8
	v_sub_u32_e32 v2, v2, v4
	v_or3_b32 v6, v6, v7, v8
	v_lshlrev_b32_e32 v7, 5, v0
	v_ashrrev_i16_sdwa v2, v241, sext(v2) dst_sel:DWORD dst_unused:UNUSED_PAD src0_sel:DWORD src1_sel:BYTE_0
	v_and_b32_e32 v7, 32, v7
	v_bfe_i32 v2, v2, 0, 16
	v_add_lshl_u32 v4, v7, v2, 1
	v_lshl_add_u32 v164, v6, 11, v4
	v_lshl_add_u32 v166, v5, 11, v4
	v_bfe_i32 v4, v244, 27, 1
	v_lshrrev_b32_e32 v4, 22, v4
	v_add_u32_e32 v4, v3, v4
	v_and_b32_e32 v4, 0xfffffc00, v4
	v_sub_u32_e32 v3, v3, v4
	v_lshrrev_b32_e32 v4, 4, v3
	v_bitop3_b32 v5, v4, v3, 32 bitop3:0x6c
	v_ashrrev_i32_e32 v4, 31, v244
	v_lshrrev_b32_e32 v4, 26, v4
	v_ashrrev_i32_e32 v3, 31, v3
	v_add_u32_e32 v4, v244, v4
	v_lshrrev_b32_e32 v3, 26, v3
	v_ashrrev_i32_e32 v4, 6, v4
	v_add_u32_e32 v3, v5, v3
	v_lshlrev_b32_e32 v6, 3, v4
	v_ashrrev_i32_e32 v3, 6, v3
	v_and_b32_e32 v6, -16, v6
	v_add_u32_e32 v6, v3, v6
	v_and_b32_e32 v7, 3, v3
	v_lshrrev_b32_e32 v8, 2, v6
	v_lshlrev_b32_e32 v9, 1, v6
	v_and_or_b32 v7, v6, s10, v7
	v_and_b32_e32 v8, 4, v8
	v_and_b32_e32 v9, 24, v9
	v_or3_b32 v7, v7, v8, v9
	v_mul_i32_i24_e32 v9, 64, v3
	v_sub_u32_e32 v5, v5, v9
	s_addc_u32 s68, s11, 0
	v_lshlrev_b32_e32 v8, 5, v4
	v_ashrrev_i16_sdwa v5, v241, sext(v5) dst_sel:DWORD dst_unused:UNUSED_PAD src0_sel:DWORD src1_sel:BYTE_0
	v_readlane_b32 s10, v255, 15
	v_and_b32_e32 v8, 32, v8
	v_bfe_i32 v5, v5, 0, 16
	v_readlane_b32 s11, v255, 16
	s_add_u32 s10, s63, s10
	v_add_lshl_u32 v8, v8, v5, 1
	s_addc_u32 s11, s68, s11
	s_add_i32 s69, s58, 0
	v_lshl_add_u32 v174, v7, 11, v8
	s_add_i32 m0, s69, 0x10000
	v_readlane_b32 s12, v255, 13
	global_load_lds_dwordx4 v174, s[10:11]
	s_add_i32 m0, s69, 0x12000
	v_readlane_b32 s13, v255, 14
	s_add_u32 s12, s59, s12
	v_lshl_add_u32 v182, v6, 11, v8
	global_load_lds_dwordx4 v164, s[10:11]
	s_addc_u32 s13, s62, s13
	s_mov_b32 m0, s69
	s_add_i32 s75, s69, 0x2000
	global_load_lds_dwordx4 v182, s[12:13]
	s_mov_b32 m0, s75
	s_add_u32 s20, s10, 0x40000
	global_load_lds_dwordx4 v166, s[12:13]
	s_addc_u32 s21, s11, 0
	s_add_i32 m0, s69, 0x14000
	s_nop 0
	global_load_lds_dwordx4 v174, s[20:21]
	s_add_i32 m0, s69, 0x16000
	s_nop 0
	global_load_lds_dwordx4 v164, s[20:21]
	s_add_u32 s20, s12, 0x40000
	s_addc_u32 s21, s13, 0
	s_add_i32 s76, s69, 0x4000
	s_mov_b32 m0, s76
	s_add_i32 s77, s69, 0x6000
	global_load_lds_dwordx4 v182, s[20:21]
	s_mov_b32 m0, s77
	global_load_lds_dwordx4 v166, s[20:21]
	v_and_b32_e32 v67, 64, v237
	s_waitcnt vmcnt(8)
	v_pk_add_f32 v[60:61], v[60:61], v[62:63]
	v_xor_b32_e32 v64, 1, v237
	v_add_u32_e32 v67, 64, v67
	v_pk_add_f32 v[60:61], v[60:61], 0 op_sel_hi:[1,0]
	v_pk_add_f32 v[56:57], v[56:57], v[58:59]
	v_cmp_lt_i32_e32 vcc, v64, v67
	v_pk_add_f32 v[56:57], v[60:61], v[56:57]
	v_pk_add_f32 v[52:53], v[52:53], v[54:55]
	v_cndmask_b32_e32 v64, v237, v64, vcc
	v_pk_add_f32 v[52:53], v[56:57], v[52:53]
	v_pk_add_f32 v[48:49], v[48:49], v[50:51]
	v_lshlrev_b32_e32 v64, 2, v64
	v_pk_add_f32 v[48:49], v[52:53], v[48:49]
	ds_bpermute_b32 v50, v64, v48
	ds_bpermute_b32 v51, v64, v49
	v_cmp_eq_u32_e32 vcc, 0, v66
	v_lshl_add_u32 v52, v65, 3, s90
	s_and_saveexec_b64 s[100:101], vcc
	s_cbranch_execz .Lpo_g1e_wo
	s_waitcnt lgkmcnt(0)
	v_pk_add_f32 v[48:49], v[48:49], v[50:51]
	s_nop 0
	v_pk_mul_f32 v[48:49], v[48:49], s[6:7] op_sel_hi:[1,0]
	s_nop 0
	v_fma_f32 v49, -v48, v48, v49
	v_max_f32_e32 v49, 0, v49
	v_add_f32_e32 v49, 0x3727c5ac, v49
	v_mul_f32_e32 v50, 0x4b800000, v49
	v_cmp_gt_f32_e64 s[24:25], s14, v49
	s_nop 1
	v_cndmask_b32_e64 v49, v49, v50, s[24:25]
	v_rsq_f32_e32 v49, v49
	s_nop 0
	v_mul_f32_e32 v50, 0x45800000, v49
	v_cndmask_b32_e64 v49, v49, v50, s[24:25]
	ds_write_b64 v52, v[48:49]
.Lpo_g1e_wo:
	s_or_b64 exec, exec, s[100:101]
	s_waitcnt lgkmcnt(0)
	s_barrier
	s_cmp_lg_u32 s16, 1
	s_branch .Lpo_cont_wo

.Lpo_cont_wo:
	s_cbranch_scc1 .LBB0_1045
	s_barrier

.Lst_skip_f2:
	v_readlane_b32 s100, v255, 57
	s_ashr_i32 s75, s74, 31
	v_readlane_b32 s101, v255, 58
	s_lshl_b64 s[30:31], s[74:75], 23
	v_readfirstlane_b32 s46, v219
	s_and_b64 vcc, exec, s[100:101]
	v_and_b32_e32 v220, 15, v219
	s_cbranch_vccnz .Lpo_old_f2
	v_lshlrev_b32_e32 v3, 4, v219
	v_add_u32_e32 v1, 0x2000, v3
	v_ashrrev_i32_e32 v0, 31, v1
	v_lshrrev_b32_e32 v0, 22, v0
	v_add_u32_e32 v0, v1, v0
	v_ashrrev_i32_e32 v0, 10, v0
	v_mul_i32_i24_e32 v2, 0x400, v0
	v_sub_u32_e32 v1, v1, v2
	v_lshrrev_b32_e32 v2, 4, v1
	s_ashr_i32 s17, s46, 6
	v_bitop3_b32 v2, v2, v1, 32 bitop3:0x6c
	s_ashr_i32 s16, s46, 8
	s_lshl_b32 s47, s17, 10
	v_ashrrev_i32_e32 v1, 31, v2
	s_add_u32 s48, s28, 0x6a80000
	v_lshrrev_b32_e32 v1, 26, v1
	s_addc_u32 s49, s29, 0
	v_add_u32_e32 v4, v2, v1
	v_lshlrev_b32_e32 v5, 3, v0
	s_add_u32 s10, s28, s30
	v_ashrrev_i32_e32 v1, 6, v4
	v_and_b32_e32 v5, -16, v5
	s_addc_u32 s11, s29, s31
	v_add_u32_e32 v5, v1, v5
	s_add_u32 s50, s10, 0x1a00000
	v_and_b32_e32 v6, 3, v1
	s_mov_b32 s10, 0x7ffe0
	v_lshrrev_b32_e32 v7, 2, v5
	v_lshlrev_b32_e32 v8, 1, v5
	v_and_b32_e32 v4, 0xc0, v4
	v_and_or_b32 v6, v5, s10, v6
	v_and_b32_e32 v7, 4, v7
	v_and_b32_e32 v8, 24, v8
	v_sub_u32_e32 v2, v2, v4
	v_or3_b32 v6, v6, v7, v8
	v_lshlrev_b32_e32 v7, 5, v0
	v_ashrrev_i16_sdwa v2, v241, sext(v2) dst_sel:DWORD dst_unused:UNUSED_PAD src0_sel:DWORD src1_sel:BYTE_0
	v_and_b32_e32 v7, 32, v7
	v_bfe_i32 v2, v2, 0, 16
	v_add_lshl_u32 v4, v7, v2, 1
	v_lshl_add_u32 v182, v6, 13, v4
	v_lshl_add_u32 v184, v5, 13, v4
	v_bfe_i32 v4, v219, 27, 1
	v_lshrrev_b32_e32 v4, 22, v4
	v_add_u32_e32 v4, v3, v4
	v_and_b32_e32 v4, 0xfffffc00, v4
	v_sub_u32_e32 v3, v3, v4
	v_lshrrev_b32_e32 v4, 4, v3
	v_bitop3_b32 v5, v4, v3, 32 bitop3:0x6c
	v_ashrrev_i32_e32 v4, 31, v219
	v_lshrrev_b32_e32 v4, 26, v4
	v_ashrrev_i32_e32 v3, 31, v3
	v_add_u32_e32 v4, v219, v4
	v_lshrrev_b32_e32 v3, 26, v3
	v_ashrrev_i32_e32 v4, 6, v4
	v_add_u32_e32 v3, v5, v3
	v_lshlrev_b32_e32 v6, 3, v4
	v_ashrrev_i32_e32 v3, 6, v3
	v_and_b32_e32 v6, -16, v6
	v_add_u32_e32 v6, v3, v6
	v_and_b32_e32 v7, 3, v3
	v_lshrrev_b32_e32 v8, 2, v6
	v_lshlrev_b32_e32 v9, 1, v6
	v_and_or_b32 v7, v6, s10, v7
	v_and_b32_e32 v8, 4, v8
	v_and_b32_e32 v9, 24, v9
	v_or3_b32 v7, v7, v8, v9
	v_mul_i32_i24_e32 v9, 64, v3
	v_sub_u32_e32 v5, v5, v9
	s_addc_u32 s51, s11, 0
	v_lshlrev_b32_e32 v8, 5, v4
	v_ashrrev_i16_sdwa v5, v241, sext(v5) dst_sel:DWORD dst_unused:UNUSED_PAD src0_sel:DWORD src1_sel:BYTE_0
	v_readlane_b32 s10, v255, 20
	v_and_b32_e32 v8, 32, v8
	v_bfe_i32 v5, v5, 0, 16
	v_readlane_b32 s11, v255, 21
	s_add_u32 s10, s50, s10
	v_add_lshl_u32 v8, v8, v5, 1
	s_addc_u32 s11, s51, s11
	s_add_i32 s54, s47, 0
	v_lshl_add_u32 v174, v7, 13, v8
	s_add_i32 m0, s54, 0x10000
	v_readlane_b32 s12, v255, 24
	global_load_lds_dwordx4 v174, s[10:11]
	s_add_i32 m0, s54, 0x12000
	v_readlane_b32 s13, v255, 25
	s_add_u32 s12, s48, s12
	v_lshl_add_u32 v186, v6, 13, v8
	global_load_lds_dwordx4 v182, s[10:11]
	s_addc_u32 s13, s49, s13
	s_mov_b32 m0, s54
	s_add_i32 s55, s54, 0x2000
	global_load_lds_dwordx4 v186, s[12:13]
	s_mov_b32 m0, s55
	s_add_u32 s20, s10, 0x100000
	global_load_lds_dwordx4 v184, s[12:13]
	s_addc_u32 s21, s11, 0
	s_add_i32 m0, s54, 0x14000
	s_nop 0
	global_load_lds_dwordx4 v174, s[20:21]
	s_add_i32 m0, s54, 0x16000
	s_nop 0
	global_load_lds_dwordx4 v182, s[20:21]
	s_add_u32 s20, s12, 0x100000
	s_addc_u32 s21, s13, 0
	s_add_i32 s58, s54, 0x4000
	s_mov_b32 m0, s58
	s_add_i32 s59, s54, 0x6000
	global_load_lds_dwordx4 v186, s[20:21]
	s_mov_b32 m0, s59
	global_load_lds_dwordx4 v184, s[20:21]
	s_waitcnt vmcnt(8)
	v_pk_add_f32 v[60:61], v[60:61], v[62:63]
	v_pk_add_f32 v[56:57], v[56:57], v[58:59]
	v_pk_add_f32 v[60:61], v[60:61], 0 op_sel_hi:[1,0]
	v_pk_add_f32 v[52:53], v[52:53], v[54:55]
	v_pk_add_f32 v[56:57], v[60:61], v[56:57]
	v_pk_add_f32 v[48:49], v[48:49], v[50:51]
	v_pk_add_f32 v[52:53], v[56:57], v[52:53]
	v_cmp_eq_u32_e32 vcc, 0, v65
	v_pk_add_f32 v[48:49], v[52:53], v[48:49]
	ds_bpermute_b32 v50, v200, v48
	ds_bpermute_b32 v51, v200, v49
	v_lshl_add_u32 v52, v64, 3, s90
	s_and_saveexec_b64 s[100:101], vcc
	s_cbranch_execz .Lpo_g1e_f2
	s_waitcnt lgkmcnt(0)
	v_pk_add_f32 v[48:49], v[48:49], v[50:51]
	s_nop 0
	v_pk_mul_f32 v[48:49], v[48:49], s[6:7] op_sel_hi:[1,0]
	s_nop 0
	v_fma_f32 v49, -v48, v48, v49
	v_max_f32_e32 v49, 0, v49
	v_add_f32_e32 v49, 0x3727c5ac, v49
	v_mul_f32_e32 v50, 0x4b800000, v49
	v_cmp_gt_f32_e64 s[22:23], s14, v49
	s_nop 1
	v_cndmask_b32_e64 v49, v49, v50, s[22:23]
	v_rsq_f32_e32 v49, v49
	s_nop 0
	v_mul_f32_e32 v50, 0x45800000, v49
	v_cndmask_b32_e64 v49, v49, v50, s[22:23]
	ds_write_b64 v52, v[48:49]
